# hot loop heads (w_out/down and w_in GEMM k-loops, attention key-tile loops) aligned to 64 bytes
# speedup vs baseline: 1.0019x; 1.0019x over previous
.LBB0_88:
	s_lshl_b32 s11, s16, 7
	s_and_b32 s27, s11, 0x1f80
	v_add_u32_e32 v5, s27, v86
	v_mad_i64_i32 v[2:3], s[38:39], v5, s13, 0
	s_lshl_b32 s11, s16, 1
	s_and_b32 s38, s11, 0xffffff80
	v_add_u32_e32 v4, s38, v86
	v_add_u32_e32 v14, 0, v87
	v_min_i32_e32 v6, 0x3ff, v4
	v_readfirstlane_b32 s11, v14
	v_add_u32_e32 v15, 0x8000, v14
	v_mad_i64_i32 v[6:7], s[40:41], v6, s13, 0
	v_lshl_add_u64 v[2:3], v[2:3], 1, v[66:67]
	s_mov_b32 m0, s11
	v_readfirstlane_b32 s11, v15
	v_add_u32_e32 v15, 0x1000, v14
	v_lshl_add_u64 v[6:7], v[6:7], 1, v[68:69]
	global_load_lds_dwordx4 v[2:3], off
	s_mov_b32 m0, s11
	v_readfirstlane_b32 s11, v15
	v_add_u32_e32 v8, 32, v4
	global_load_lds_dwordx4 v[6:7], off
	v_lshl_add_u64 v[6:7], v[2:3], 0, s[92:93]
	s_mov_b32 m0, s11
	v_min_i32_e32 v8, 0x3ff, v8
	global_load_lds_dwordx4 v[6:7], off
	v_add_u32_e32 v6, 0x9000, v14
	v_mad_i64_i32 v[8:9], s[40:41], v8, s13, 0
	v_readfirstlane_b32 s11, v6
	v_lshl_add_u64 v[8:9], v[8:9], 1, v[68:69]
	s_mov_b32 m0, s11
	s_mov_b32 s11, s93
	global_load_lds_dwordx4 v[8:9], off
	v_add_u32_e32 v8, 0x2000, v14
	v_lshl_add_u64 v[6:7], v[2:3], 0, s[10:11]
	v_readfirstlane_b32 s11, v8
	v_add_u32_e32 v10, 64, v4
	s_mov_b32 m0, s11
	v_min_i32_e32 v10, 0x3ff, v10
	global_load_lds_dwordx4 v[6:7], off
	v_add_u32_e32 v6, 0xa000, v14
	v_mad_i64_i32 v[10:11], s[40:41], v10, s13, 0
	v_readfirstlane_b32 s11, v6
	v_add_u32_e32 v6, 0x3000, v14
	v_lshl_add_u64 v[10:11], v[10:11], 1, v[68:69]
	s_mov_b32 m0, s11
	s_mov_b32 s37, s93
	v_readfirstlane_b32 s11, v6
	v_add_u32_e32 v12, 0x60, v4
	global_load_lds_dwordx4 v[10:11], off
	v_lshl_add_u64 v[2:3], v[2:3], 0, s[36:37]
	s_mov_b32 m0, s11
	v_min_i32_e32 v12, 0x3ff, v12
	global_load_lds_dwordx4 v[2:3], off
	v_add_u32_e32 v2, 0xb000, v14
	v_mad_i64_i32 v[12:13], s[40:41], v12, s13, 0
	v_readfirstlane_b32 s11, v2
	v_lshl_add_u64 v[12:13], v[12:13], 1, v[68:69]
	s_mov_b32 m0, s11
	v_mov_b64_e32 v[2:3], s[4:5]
	global_load_lds_dwordx4 v[12:13], off
	v_mad_i64_i32 v[70:71], s[40:41], s25, v5, v[2:3]
	v_lshlrev_b32_e32 v5, 1, v5
	v_add_u32_e32 v6, 64, v5
	v_mad_i64_i32 v[72:73], s[40:41], s13, v6, v[2:3]
	v_add_u32_e32 v6, 0x80, v5
	v_add_u32_e32 v5, 0xc0, v5
	v_mad_i64_i32 v[76:77], s[40:41], s13, v5, v[2:3]
	v_ashrrev_i32_e32 v5, 31, v4
	s_mov_b64 s[42:43], 0x3ff
	v_cmp_gt_i64_e32 vcc, s[42:43], v[4:5]
	v_mad_i64_i32 v[74:75], s[40:41], s13, v6, v[2:3]
	s_nop 0
	v_cndmask_b32_e32 v4, v199, v4, vcc
	v_mov_b64_e32 v[2:3], s[6:7]
	v_mad_i64_i32 v[78:79], s[40:41], s25, v4, v[2:3]
	v_add_u32_e32 v4, s38, v97
	v_ashrrev_i32_e32 v5, 31, v4
	v_cmp_gt_i64_e32 vcc, s[42:43], v[4:5]
	s_waitcnt vmcnt(0)
	s_movk_i32 s11, 0x4000
	s_waitcnt vmcnt(0) lgkmcnt(0)
	v_cndmask_b32_e32 v4, v199, v4, vcc
	v_mad_i64_i32 v[80:81], s[40:41], s25, v4, v[2:3]
	v_add_u32_e32 v4, s38, v98
	v_ashrrev_i32_e32 v5, 31, v4
	v_cmp_gt_i64_e32 vcc, s[42:43], v[4:5]
	s_barrier
	s_nop 0
	v_cndmask_b32_e32 v4, v199, v4, vcc
	v_mad_i64_i32 v[82:83], s[40:41], s25, v4, v[2:3]
	v_add_u32_e32 v4, s38, v99
	v_ashrrev_i32_e32 v5, 31, v4
	v_cmp_gt_i64_e32 vcc, s[42:43], v[4:5]
	s_nop 1
	v_cndmask_b32_e32 v4, v199, v4, vcc
	v_mad_i64_i32 v[84:85], s[40:41], s25, v4, v[2:3]
	v_mov_b32_e32 v2, 0
	v_mov_b32_e32 v3, v2
	v_mov_b32_e32 v4, v2
	v_mov_b32_e32 v5, v2
	v_mov_b32_e32 v6, v2
	v_mov_b32_e32 v7, v2
	v_mov_b32_e32 v8, v2
	v_mov_b32_e32 v9, v2
	v_mov_b32_e32 v10, v2
	v_mov_b32_e32 v11, v2
	v_mov_b32_e32 v12, v2
	v_mov_b32_e32 v13, v2
	v_mov_b32_e32 v14, v2
	v_mov_b32_e32 v15, v2
	v_mov_b32_e32 v16, v2
	v_mov_b32_e32 v17, v2
	v_mov_b32_e32 v18, v2
	v_mov_b32_e32 v19, v2
	v_mov_b32_e32 v20, v2
	v_mov_b32_e32 v21, v2
	v_mov_b32_e32 v22, v2
	v_mov_b32_e32 v23, v2
	v_mov_b32_e32 v24, v2
	v_mov_b32_e32 v25, v2
	v_mov_b32_e32 v26, v2
	v_mov_b32_e32 v27, v2
	v_mov_b32_e32 v28, v2
	v_mov_b32_e32 v29, v2
	v_mov_b32_e32 v30, v2
	v_mov_b32_e32 v31, v2
	v_mov_b32_e32 v32, v2
	v_mov_b32_e32 v33, v2
	v_mov_b32_e32 v34, v2
	v_mov_b32_e32 v35, v2
	v_mov_b32_e32 v36, v2
	v_mov_b32_e32 v37, v2
	v_mov_b32_e32 v38, v2
	v_mov_b32_e32 v39, v2
	v_mov_b32_e32 v40, v2
	v_mov_b32_e32 v41, v2
	v_mov_b32_e32 v42, v2
	v_mov_b32_e32 v43, v2
	v_mov_b32_e32 v44, v2
	v_mov_b32_e32 v45, v2
	v_mov_b32_e32 v46, v2
	v_mov_b32_e32 v47, v2
	v_mov_b32_e32 v48, v2
	v_mov_b32_e32 v49, v2
	v_mov_b32_e32 v50, v2
	v_mov_b32_e32 v51, v2
	v_mov_b32_e32 v52, v2
	v_mov_b32_e32 v53, v2
	v_mov_b32_e32 v54, v2
	v_mov_b32_e32 v55, v2
	v_mov_b32_e32 v56, v2
	v_mov_b32_e32 v57, v2
	v_mov_b32_e32 v58, v2
	v_mov_b32_e32 v59, v2
	v_mov_b32_e32 v60, v2
	v_mov_b32_e32 v61, v2
	v_mov_b32_e32 v62, v2
	v_mov_b32_e32 v63, v2
	v_mov_b32_e32 v64, v2
	v_mov_b32_e32 v65, v2
	v_readfirstlane_b32 s37, v87
	s_lshr_b32 s39, s22, 15
	s_sub_u32 s39, s39, 1
	v_lshl_add_u64 v[70:71], v[70:71], 0, v[130:131]
	v_lshl_add_u64 v[72:73], v[72:73], 0, v[130:131]
	v_lshl_add_u64 v[74:75], v[74:75], 0, v[130:131]
	v_lshl_add_u64 v[76:77], v[76:77], 0, v[130:131]
	v_lshl_add_u64 v[78:79], v[78:79], 0, v[130:131]
	v_lshl_add_u64 v[80:81], v[80:81], 0, v[130:131]
	v_lshl_add_u64 v[82:83], v[82:83], 0, v[130:131]
	v_lshl_add_u64 v[84:85], v[84:85], 0, v[130:131]
	v_add3_u32 v116, v88, v89, v90
	v_add_u32_e32 v120, v88, v92
	v_add3_u32 v117, v93, v89, v90
	v_add_u32_e32 v121, v93, v92
	v_add3_u32 v118, v94, v89, v90
	v_add_u32_e32 v122, v94, v92
	v_add3_u32 v119, v95, v89, v90
	v_add_u32_e32 v123, v95, v92
	ds_read_b128 v[132:135], v116
	ds_read_b128 v[136:139], v116 offset:4096
	ds_read_b128 v[140:143], v120 offset:32768
	ds_read_b128 v[144:147], v120 offset:40960
	.p2align 6

.LBB0_199:
	v_lshlrev_b64 v[2:3], 7, v[2:3]
	v_lshlrev_b64 v[116:117], 1, v[2:3]
	v_add_u32_e32 v12, 0x2000, v8
	v_lshl_add_u64 v[2:3], s[36:37], 0, v[116:117]
	v_readfirstlane_b32 s7, v12
	v_lshlrev_b32_e32 v10, 3, v10
	v_lshl_add_u64 v[2:3], v[2:3], 0, v[130:131]
	s_mov_b32 m0, s7
	v_add_u32_e32 v8, 0x8000, v8
	v_lshlrev_b64 v[4:5], 7, v[4:5]
	global_load_lds_dwordx4 v[2:3], off
	v_lshl_add_u64 v[2:3], s[38:39], 0, v[116:117]
	v_lshlrev_b32_e32 v118, 1, v10
	v_mov_b32_e32 v119, v131
	v_readfirstlane_b32 s7, v8
	v_lshl_add_u64 v[2:3], v[2:3], 0, v[118:119]
	s_mov_b32 m0, s7
	v_lshlrev_b64 v[120:121], 1, v[4:5]
	v_add_u32_e32 v4, 0x2000, v9
	global_load_lds_dwordx4 v[2:3], off
	v_lshl_add_u64 v[2:3], s[36:37], 0, v[120:121]
	v_mov_b32_e32 v115, v131
	v_readfirstlane_b32 s7, v4
	v_lshlrev_b32_e32 v11, 3, v11
	v_lshl_add_u64 v[2:3], v[2:3], 0, v[114:115]
	s_mov_b32 m0, s7
	v_add_u32_e32 v4, 0x8000, v9
	global_load_lds_dwordx4 v[2:3], off
	v_lshl_add_u64 v[2:3], s[38:39], 0, v[120:121]
	v_lshlrev_b32_e32 v122, 1, v11
	v_mov_b32_e32 v123, v131
	v_readfirstlane_b32 s7, v4
	v_lshl_add_u64 v[2:3], v[2:3], 0, v[122:123]
	s_mov_b32 m0, s7
	s_lshl_b64 s[36:37], s[92:93], 1
	global_load_lds_dwordx4 v[2:3], off
	v_readlane_b32 s38, v253, 40
	v_readlane_b32 s39, v253, 41
	s_add_u32 s44, s38, s36
	s_addc_u32 s45, s39, s37
	v_readlane_b32 s38, v253, 34
	v_lshrrev_b32_e32 v2, 1, v6
	v_bfe_u32 v3, v6, 1, 3
	v_bfe_u32 v4, v6, 2, 2
	v_lshrrev_b32_e32 v5, 3, v6
	v_lshlrev_b32_e32 v8, 3, v6
	v_bfe_u32 v6, v6, 1, 1
	v_readlane_b32 s39, v253, 35
	s_add_u32 s46, s38, s36
	v_and_or_b32 v4, v5, 4, v4
	v_and_or_b32 v5, v5, 2, v6
	s_addc_u32 s47, s39, s37
	s_lshl_b32 s7, s48, 14
	v_and_or_b32 v6, v2, 4, v5
	v_bitop3_b32 v5, v5, v2, 4 bitop3:0x72
	v_bitop3_b32 v2, v205, v2, 7 bitop3:0x78
	s_add_u32 s48, s7, 0x4000
	v_lshlrev_b32_e32 v139, 4, v2
	v_bitop3_b32 v2, v205, v3, 2 bitop3:0x36
	s_add_u32 s7, s10, s36
	v_lshlrev_b32_e32 v129, 4, v2
	v_bitop3_b32 v2, v205, v3, 4 bitop3:0x36
	s_addc_u32 s10, s11, s37
	v_lshlrev_b32_e32 v4, 7, v4
	v_and_b32_e32 v8, 8, v8
	v_lshlrev_b32_e32 v128, 4, v2
	v_bitop3_b32 v2, v205, v3, 6 bitop3:0x36
	s_add_u32 s49, s62, s7
	v_mov_b32_e32 v140, 0
	s_mov_b32 s43, 2
	v_add3_u32 v124, 0, v4, v8
	v_lshl_add_u32 v137, v7, 7, 0
	v_lshlrev_b32_e32 v127, 4, v2
	v_lshlrev_b32_e32 v125, 4, v6
	v_lshlrev_b32_e32 v126, 4, v5
	s_addc_u32 s50, s63, s10
	s_mov_b32 s7, 0
	v_mov_b32_e32 v141, 0xff800000
	s_mov_b64 s[10:11], 0
	s_movk_i32 s51, 0x80
	v_mov_b32_e32 v2, 0
	v_mov_b32_e32 v3, v140
	v_mov_b32_e32 v4, v140
	v_mov_b32_e32 v5, v140
	v_mov_b32_e32 v6, v140
	v_mov_b32_e32 v7, v140
	v_mov_b32_e32 v8, v140
	v_mov_b32_e32 v9, v140
	v_mov_b32_e32 v10, v140
	v_mov_b32_e32 v11, v140
	v_mov_b32_e32 v12, v140
	v_mov_b32_e32 v13, v140
	v_mov_b32_e32 v14, v140
	v_mov_b32_e32 v15, v140
	v_mov_b32_e32 v16, v140
	v_mov_b32_e32 v17, v140
	v_mov_b32_e32 v18, 0
	v_mov_b32_e32 v19, v140
	v_mov_b32_e32 v20, v140
	v_mov_b32_e32 v21, v140
	v_mov_b32_e32 v22, v140
	v_mov_b32_e32 v23, v140
	v_mov_b32_e32 v24, v140
	v_mov_b32_e32 v25, v140
	v_mov_b32_e32 v26, v140
	v_mov_b32_e32 v27, v140
	v_mov_b32_e32 v28, v140
	v_mov_b32_e32 v29, v140
	v_mov_b32_e32 v30, v140
	v_mov_b32_e32 v31, v140
	v_mov_b32_e32 v32, v140
	v_mov_b32_e32 v33, v140
	s_waitcnt vmcnt(0)
	.p2align 6

.LBB0_212:
	s_and_b64 s[6:7], exec, s[4:5]
	s_cselect_b32 s6, s10, s25
	s_lshl_b32 s6, s6, 10
	s_addk_i32 s6, 0x1000
	s_lshl_b32 s7, s25, 8
	s_and_b64 s[4:5], exec, s[4:5]
	s_cselect_b32 s10, 16, 4
	s_cselect_b32 s6, s6, s7
	s_cmp_eq_u32 s27, 0
	s_cselect_b64 s[4:5], -1, 0
	s_ashr_i32 s36, s6, 6
	v_readlane_b32 s6, v253, 42
	v_lshlrev_b64 v[16:17], 2, v[10:11]
	v_readlane_b32 s7, v253, 43
	v_ashrrev_i32_e32 v14, 3, v12
	v_ashrrev_i32_e32 v15, 31, v14
	v_lshl_add_u64 v[12:13], s[6:7], 0, v[16:17]
	v_readlane_b32 s6, v253, 44
	v_readlane_b32 s7, v253, 45
	s_mov_b32 s11, 0
	s_and_b32 s37, s42, 7
	v_lshl_add_u64 v[14:15], v[14:15], 2, s[6:7]
	v_readlane_b32 s6, v253, 28
	v_readlane_b32 s7, v253, 29
	s_add_i32 s38, s10, -1
	s_nop 0
	v_lshl_add_u64 v[16:17], s[6:7], 0, v[16:17]
	.p2align 6

.LBB0_491:
	s_lshl_b32 s1, s6, 1
	s_and_b32 s1, s1, 0xffffff80
	v_add_u32_e32 v6, s1, v80
	v_min_i32_e32 v4, 0xa2f, v6
	v_ashrrev_i32_e32 v5, 31, v4
	v_lshlrev_b64 v[4:5], 11, v[4:5]
	v_lshl_add_u64 v[70:71], v[68:69], 0, v[4:5]
	v_add_u32_e32 v4, 32, v6
	s_lshl_b32 s0, s6, 7
	v_min_i32_e32 v4, 0xa2f, v4
	s_and_b32 s0, s0, 0x1f80
	v_ashrrev_i32_e32 v5, 31, v4
	v_add_u32_e32 v2, s0, v80
	v_lshlrev_b64 v[4:5], 11, v[4:5]
	v_ashrrev_i32_e32 v3, 31, v2
	v_lshl_add_u64 v[72:73], v[68:69], 0, v[4:5]
	v_add_u32_e32 v4, 64, v6
	v_lshlrev_b64 v[2:3], 11, v[2:3]
	v_min_i32_e32 v4, 0xa2f, v4
	v_readfirstlane_b32 s22, v83
	v_add_u32_e32 v137, 0x8000, v83
	v_ashrrev_i32_e32 v5, 31, v4
	v_lshl_add_u64 v[78:79], v[66:67], 0, v[2:3]
	s_mov_b32 m0, s22
	v_readfirstlane_b32 s24, v137
	v_add_u32_e32 v138, 0x1000, v83
	v_lshlrev_b64 v[4:5], 11, v[4:5]
	global_load_lds_dwordx4 v[78:79], off
	s_mov_b32 m0, s24
	s_mov_b64 s[4:5], 0x10000
	v_readfirstlane_b32 s25, v138
	v_add_u32_e32 v139, 0x9000, v83
	v_lshl_add_u64 v[74:75], v[68:69], 0, v[4:5]
	v_add_u32_e32 v4, 0x60, v6
	global_load_lds_dwordx4 v[70:71], off
	v_lshl_add_u64 v[2:3], v[78:79], 0, s[4:5]
	s_mov_b32 m0, s25
	v_readfirstlane_b32 s27, v139
	v_add_u32_e32 v140, 0x2000, v83
	v_min_i32_e32 v4, 0xa2f, v4
	global_load_lds_dwordx4 v[2:3], off
	s_mov_b32 m0, s27
	s_mov_b64 s[4:5], 0x20000
	v_readfirstlane_b32 s36, v140
	v_add_u32_e32 v134, 0xa000, v83
	v_ashrrev_i32_e32 v5, 31, v4
	global_load_lds_dwordx4 v[72:73], off
	v_lshl_add_u64 v[2:3], v[78:79], 0, s[4:5]
	s_mov_b32 m0, s36
	v_readfirstlane_b32 s37, v134
	v_add_u32_e32 v136, 0x3000, v83
	v_lshlrev_b64 v[4:5], 11, v[4:5]
	global_load_lds_dwordx4 v[2:3], off
	s_mov_b32 m0, s37
	s_mov_b64 s[4:5], 0x30000
	v_readfirstlane_b32 s38, v136
	v_add_u32_e32 v135, 0xb000, v83
	v_lshl_add_u64 v[76:77], v[68:69], 0, v[4:5]
	global_load_lds_dwordx4 v[74:75], off
	v_lshl_add_u64 v[2:3], v[78:79], 0, s[4:5]
	s_mov_b32 m0, s38
	v_readfirstlane_b32 s39, v135
	v_add_u32_e32 v4, 0x4000, v83
	global_load_lds_dwordx4 v[2:3], off
	s_mov_b32 m0, s39
	v_readfirstlane_b32 s4, v4
	v_add_u32_e32 v4, 0xc000, v83
	global_load_lds_dwordx4 v[76:77], off
	v_lshl_add_u64 v[2:3], v[78:79], 0, s[98:99]
	s_mov_b32 m0, s4
	v_readfirstlane_b32 s5, v4
	v_add_u32_e32 v4, 0x5000, v83
	s_waitcnt vmcnt(0)
	s_waitcnt vmcnt(0) lgkmcnt(0)
	s_barrier
	v_readlane_b32 s24, v255, 48
	s_cmp_eq_u32 s24, 1
	s_cbranch_scc1 .Lg0_pair
	v_mov_b32_e32 v2, 0
	v_mov_b32_e32 v3, 0
	v_mov_b32_e32 v4, 0
	v_mov_b32_e32 v5, 0
	v_mov_b32_e32 v6, 0
	v_mov_b32_e32 v7, 0
	v_mov_b32_e32 v8, 0
	v_mov_b32_e32 v9, 0
	v_mov_b32_e32 v10, 0
	v_mov_b32_e32 v11, 0
	v_mov_b32_e32 v12, 0
	v_mov_b32_e32 v13, 0
	v_mov_b32_e32 v14, 0
	v_mov_b32_e32 v15, 0
	v_mov_b32_e32 v16, 0
	v_mov_b32_e32 v17, 0
	v_mov_b32_e32 v18, 0
	v_mov_b32_e32 v19, 0
	v_mov_b32_e32 v20, 0
	v_mov_b32_e32 v21, 0
	v_mov_b32_e32 v22, 0
	v_mov_b32_e32 v23, 0
	v_mov_b32_e32 v24, 0
	v_mov_b32_e32 v25, 0
	v_mov_b32_e32 v26, 0
	v_mov_b32_e32 v27, 0
	v_mov_b32_e32 v28, 0
	v_mov_b32_e32 v29, 0
	v_mov_b32_e32 v30, 0
	v_mov_b32_e32 v31, 0
	v_mov_b32_e32 v32, 0
	v_mov_b32_e32 v33, 0
	v_mov_b32_e32 v34, 0
	v_mov_b32_e32 v35, 0
	v_mov_b32_e32 v36, 0
	v_mov_b32_e32 v37, 0
	v_mov_b32_e32 v38, 0
	v_mov_b32_e32 v39, 0
	v_mov_b32_e32 v40, 0
	v_mov_b32_e32 v41, 0
	v_mov_b32_e32 v42, 0
	v_mov_b32_e32 v43, 0
	v_mov_b32_e32 v44, 0
	v_mov_b32_e32 v45, 0
	v_mov_b32_e32 v46, 0
	v_mov_b32_e32 v47, 0
	v_mov_b32_e32 v48, 0
	v_mov_b32_e32 v49, 0
	v_mov_b32_e32 v50, 0
	v_mov_b32_e32 v51, 0
	v_mov_b32_e32 v52, 0
	v_mov_b32_e32 v53, 0
	v_mov_b32_e32 v54, 0
	v_mov_b32_e32 v55, 0
	v_mov_b32_e32 v56, 0
	v_mov_b32_e32 v57, 0
	v_mov_b32_e32 v58, 0
	v_mov_b32_e32 v59, 0
	v_mov_b32_e32 v60, 0
	v_mov_b32_e32 v61, 0
	v_mov_b32_e32 v62, 0
	v_mov_b32_e32 v63, 0
	v_mov_b32_e32 v64, 0
	v_mov_b32_e32 v65, 0
	v_lshl_add_u64 v[164:165], v[78:79], 0, s[98:99]
	s_mov_b64 s[10:11], 0x10080
	v_lshl_add_u64 v[166:167], v[78:79], 0, s[10:11]
	s_mov_b64 s[10:11], 0x20080
	v_lshl_add_u64 v[168:169], v[78:79], 0, s[10:11]
	s_mov_b64 s[10:11], 0x30080
	v_lshl_add_u64 v[170:171], v[78:79], 0, s[10:11]
	v_lshl_add_u64 v[172:173], v[70:71], 0, s[98:99]
	v_lshl_add_u64 v[174:175], v[72:73], 0, s[98:99]
	v_lshl_add_u64 v[176:177], v[74:75], 0, s[98:99]
	v_lshl_add_u64 v[178:179], v[76:77], 0, s[98:99]
	v_add_u32_e32 v222, v119, v85
	v_add_u32_e32 v223, v118, v85
	v_add_u32_e32 v224, v117, v85
	v_add_u32_e32 v225, v116, v85
	s_mov_b32 s24, 7
	ds_read_b128 v[180:183], v120
	ds_read_b128 v[184:187], v120 offset:4096
	ds_read_b128 v[188:191], v222 offset:32768
	ds_read_b128 v[192:195], v222 offset:40960
	.p2align 6
